# GEMM1 B-row staging permutation changed so each wave's two B halves are adjacent output columns (R stores write both halves of a 128-B line back-to-back) + widened mixer y stores
# speedup vs baseline: 1.0193x; 1.0083x over previous
; #define PG8_STAGE(bufoff, gbase, voff) do { _Pragma("unroll") for (int _i = 0; _i < 2; ++_i) \
;         __builtin_amdgcn_global_load_lds((const unsigned*)((const char*)(gbase) + (voff)[_i]), (LAS unsigned*)(lds + (bufoff) + ldsw + _i * 8192), 16, 0, 0); } while (0)
; #define PG8_WAIT_V(n) asm volatile("s_waitcnt vmcnt(" #n ")" ::: "memory")
; #define PG8_BAR __builtin_amdgcn_s_barrier()
; template <class Epi, class Sched, bool ALIGN_EPI = false, bool SP2 = true>
; DI void gemm_phase(LAS unsigned char* lds, const Gemm g, const Sched& S, const Epi& E, f32x4 (&acc)[2][2][4][2]) {
;     ...
;     const int wid = __builtin_amdgcn_readfirstlane(tid >> 6), lane = tid & 63, wr = wid >> 2, wc = wid & 3, fr = lane & 15, fq = lane >> 4;
;     const int K = g.K, nt = K / BK;
;     unsigned voffA[2], voffB[2];
; #pragma unroll
;     for (int i = 0; i < 2; ++i) { int R, C; stage_rc(tid * 16 + i * 8192, R, C); const int Rb = Epi::PERM ? ((R & ~31) + perm32(R & 31)) : R;
;         voffA[i] = (unsigned)(R * K + C) * 2u; voffB[i] = (unsigned)(Rb * K + C) * 2u; }
;     const size_t kstep = (size_t)(BK * 2);
;     const size_t hstep = (size_t)HALF * K * 2;
;     const size_t tstep = 2 * hstep;
;     const unsigned ldsw = (unsigned)wid * 1024u;
;     const int aoff = lds_byte(wr * 64 + fr, fq * 8), boff = lds_byte(wc * 32 + fr, fq * 8);
;     ...
;     Unit cur, nxt; int ui = 0;
;     if (!S.next(0, cur)) return;
;     bf16x8 At[4][2], B0[2][2], B1[2][2];
;     const char* cA = (const char*)g.A + (size_t)cur.pm * tstep; const char* cB = (const char*)g.Bt + (size_t)cur.pn * tstep;
;     if constexpr (SP2) {
;         PG8_STAGE(PG8_SB(0, 0), cB, voffB); PG8_STAGE(PG8_SB(0, 1), cB + hstep, voffB); PG8_STAGE(PG8_SA(0, 0), cA, voffA); PG8_STAGE(PG8_SA(0, 1), cA + hstep, voffA);
;         if (wr == 1) PG8_BAR;
;         PG8_WAIT_V(2); PG8_BAR;
;         PG8_STAGE(PG8_SB(1, 0), cB + kstep, voffB); PG8_STAGE(PG8_SA(1, 0), cA + kstep, voffA); PG8_STAGE(PG8_SB(1, 1), cB + hstep + kstep, voffB);
;         PG8_WAIT_V(6); PG8_BAR;
.LBB0_137:
	s_add_u32 s8, s68, 0x4a80000
	s_addc_u32 s9, s69, 0
	s_add_u32 s4, s68, 0x9a80000
	s_addc_u32 s5, s69, 0
	s_add_u32 s10, s68, 0x2a80000
	s_load_dword s33, s[0:1], 0x78
	s_addc_u32 s11, s69, 0
	s_add_u32 s44, s68, 0x5a80000
	s_addc_u32 s45, s69, 0
	s_add_u32 s46, s68, 0x9aa0000
	s_addc_u32 s47, s69, 0
	s_andn2_b64 vcc, exec, s[14:15]
	s_cbranch_vccnz .LBB0_342
	v_ashrrev_i32_e32 v1, 31, v8
	v_lshrrev_b32_e32 v1, 26, v1
	v_add_u32_e32 v1, v8, v1
	v_ashrrev_i32_e32 v9, 6, v1
	v_bfe_i32 v1, v8, 27, 1
	v_lshlrev_b32_e32 v0, 4, v8
	v_lshrrev_b32_e32 v1, 22, v1
	v_add_u32_e32 v1, v0, v1
	v_and_b32_e32 v1, 0xfffffc00, v1
	v_sub_u32_e32 v1, v0, v1
	v_lshrrev_b32_e32 v2, 4, v1
	v_bitop3_b32 v1, v2, v1, 32 bitop3:0x6c
	v_ashrrev_i32_e32 v3, 31, v1
	v_lshrrev_b32_e32 v3, 26, v3
	v_add_u32_e32 v3, v1, v3
	v_lshlrev_b32_e32 v2, 3, v9
	v_ashrrev_i32_e32 v10, 6, v3
	v_and_b32_e32 v3, 0xc0, v3
	v_and_b32_e32 v2, -16, v2
	v_sub_u32_e32 v1, v1, v3
	v_mov_b32_e32 v3, 1
	v_add_u32_e32 v2, v10, v2
	v_ashrrev_i16_sdwa v1, v3, sext(v1) dst_sel:DWORD dst_unused:UNUSED_PAD src0_sel:DWORD src1_sel:BYTE_0
	v_lshlrev_b32_e32 v4, 5, v9
	v_bfe_i32 v11, v1, 0, 16
	v_lshlrev_b32_e32 v1, 1, v2
	v_lshrrev_b32_e32 v5, 2, v2
	v_and_b32_e32 v6, 3, v10
	s_mov_b32 s0, 0x1fffe0
	v_and_b32_e32 v4, 32, v4
	v_and_b32_e32 v1, 24, v1
	v_and_b32_e32 v5, 4, v5
	v_and_or_b32 v6, v2, s0, v6
	v_or3_b32 v1, v6, v5, v1
	v_add_lshl_u32 v4, v4, v11, 1
	v_add_u32_e32 v0, 0x2000, v0
	v_lshl_add_u32 v130, v1, 11, v4
	v_lshrrev_b32_e32 v1, 8, v8
	v_lshl_add_u32 v130, v1, 16, v130
	v_ashrrev_i32_e32 v1, 31, v0
	v_lshrrev_b32_e32 v1, 22, v1
	v_add_u32_e32 v1, v0, v1
	v_ashrrev_i32_e32 v12, 10, v1
	v_mul_i32_i24_e32 v1, 0x400, v12
	v_sub_u32_e32 v0, v0, v1
	v_lshrrev_b32_e32 v1, 4, v0
	v_bitop3_b32 v0, v1, v0, 32 bitop3:0x6c
	v_lshl_add_u32 v128, v2, 11, v4
	v_ashrrev_i32_e32 v2, 31, v0
	v_lshrrev_b32_e32 v2, 26, v2
	v_add_u32_e32 v2, v0, v2
	v_lshlrev_b32_e32 v1, 3, v12
	v_ashrrev_i32_e32 v13, 6, v2
	v_and_b32_e32 v2, 0xc0, v2
	v_and_b32_e32 v1, -16, v1
	v_sub_u32_e32 v0, v0, v2
	v_add_u32_e32 v1, v13, v1
	v_ashrrev_i16_sdwa v0, v3, sext(v0) dst_sel:DWORD dst_unused:UNUSED_PAD src0_sel:DWORD src1_sel:BYTE_0
	v_and_b32_e32 v3, 3, v13
	s_ashr_i32 s14, s18, 6
	s_ashr_i32 s17, s16, 31
	s_ashr_i32 s13, s12, 31
	s_ashr_i32 s19, s18, 8
	v_and_or_b32 v3, v1, s0, v3
	s_lshl_b32 s39, s14, 10
	s_lshl_b64 s[0:1], s[16:17], 19
	s_lshl_b64 s[12:13], s[12:13], 19
	s_add_u32 s30, s68, s12
	v_lshlrev_b32_e32 v4, 5, v12
	v_bfe_i32 v14, v0, 0, 16
	v_lshlrev_b32_e32 v0, 1, v1
	v_lshrrev_b32_e32 v2, 2, v1
	s_addc_u32 s31, s69, s13
	s_add_i32 s74, s39, 0
	v_and_b32_e32 v4, 32, v4
	v_and_b32_e32 v0, 24, v0
	v_and_b32_e32 v2, 4, v2
	s_add_i32 m0, s74, 0x10000
	v_or3_b32 v0, v3, v2, v0
	v_add_lshl_u32 v2, v4, v14, 1
	global_load_lds_dwordx4 v130, s[30:31]
	s_add_i32 m0, s74, 0x12000
	v_lshl_add_u32 v134, v0, 11, v2
	v_lshrrev_b32_e32 v0, 8, v8
	v_lshl_add_u32 v134, v0, 16, v134
	v_add_u32_e32 v134, 0x20000, v134
	s_add_u32 s12, s30, 0x10000
	global_load_lds_dwordx4 v134, s[30:31]
	s_addc_u32 s13, s31, 0
	s_add_i32 m0, s74, 0x14000
	v_lshl_add_u32 v132, v1, 11, v2
	global_load_lds_dwordx4 v130, s[12:13]
	s_add_i32 m0, s74, 0x16000
	s_add_u32 s0, s68, s0
	s_addc_u32 s1, s69, s1
	s_add_i32 s75, s74, 0x2000
	global_load_lds_dwordx4 v134, s[12:13]
	s_mov_b32 m0, s74
	s_add_u32 s12, s0, 0x40000
	global_load_lds_dwordx4 v128, s[0:1]
	s_mov_b32 m0, s75
	s_addc_u32 s13, s1, 0
	s_add_i32 s76, s74, 0x4000
	global_load_lds_dwordx4 v132, s[0:1]
	s_mov_b32 m0, s76
	s_add_i32 s77, s74, 0x6000
	global_load_lds_dwordx4 v128, s[12:13]
	s_mov_b32 m0, s77
	v_mov_b32_e32 v131, 0
	global_load_lds_dwordx4 v132, s[12:13]
	v_mov_b32_e32 v135, v131
	v_mov_b32_e32 v129, v131
	v_mov_b32_e32 v133, v131
	s_cmp_eq_u32 s19, 1
	s_mov_b32 s78, 0
	v_lshl_add_u64 v[6:7], s[30:31], 0, v[130:131]
	v_lshl_add_u64 v[4:5], s[30:31], 0, v[134:135]
	v_lshl_add_u64 v[0:1], s[0:1], 0, v[128:129]
	s_cselect_b64 s[12:13], -1, 0
	s_cmp_lg_u32 s19, 1
	v_lshl_add_u64 v[2:3], s[0:1], 0, v[132:133]
	s_cbranch_scc1 .LBB0_140
	s_barrier
.LBB0_140:
	s_lshl_b32 s14, s14, 5
	s_and_b32 s79, s14, 0x60
	s_mov_b64 s[14:15], 0x80
	s_add_i32 m0, s74, 0x18000
	v_lshl_add_u64 v[6:7], v[6:7], 0, s[14:15]
	s_lshl_b32 s20, s19, 13
	s_lshl_b32 s21, s79, 7
	s_waitcnt vmcnt(2)
	s_barrier
	global_load_lds_dwordx4 v[6:7], off
	v_lshl_add_u64 v[4:5], v[4:5], 0, s[14:15]
	s_add_i32 m0, s74, 0x1a000
	s_add_i32 s80, s74, 0x8000
	s_add_i32 s81, s74, 0xa000
	global_load_lds_dwordx4 v[4:5], off
	v_lshl_add_u64 v[0:1], v[0:1], 0, s[14:15]
	s_mov_b32 m0, s80
	s_add_u32 s16, s30, 0x10080
	global_load_lds_dwordx4 v[0:1], off
	v_lshl_add_u64 v[0:1], v[2:3], 0, s[14:15]
	s_mov_b32 m0, s81
	s_addc_u32 s17, s31, 0
	global_load_lds_dwordx4 v[0:1], off
	s_add_i32 m0, s74, 0x1c000
	v_lshl_add_u64 v[0:1], s[16:17], 0, v[130:131]
	global_load_lds_dwordx4 v[0:1], off
	v_lshl_add_u64 v[0:1], s[16:17], 0, v[134:135]
	s_add_i32 m0, s74, 0x1e000
	v_and_b32_e32 v139, 15, v8
	global_load_lds_dwordx4 v[0:1], off
	v_bfe_u32 v1, v8, 4, 2
	v_lshlrev_b32_e32 v136, 3, v1
	v_lshlrev_b32_e32 v1, 4, v1
	v_lshlrev_b32_e32 v2, 2, v8
	v_lshl_or_b32 v1, v139, 6, v1
	v_and_b32_e32 v2, 32, v2
	v_lshrrev_b32_e32 v0, 4, v8
	v_bitop3_b32 v3, v1, s20, v2 bitop3:0xde
	v_bitop3_b32 v143, v1, s21, v2 bitop3:0xde
	v_lshrrev_b32_e32 v1, 1, v8
	v_bfe_u32 v138, v0, 1, 1
	v_lshlrev_b32_e32 v0, 1, v8
	v_and_b32_e32 v1, 4, v1
	v_and_b32_e32 v140, 32, v0
	v_and_or_b32 v145, v0, 8, v1
	v_lshlrev_b32_e32 v0, 14, v9
	v_and_b32_e32 v0, 0xffff8000, v0
	v_lshl_add_u32 v0, v10, 11, v0
	v_and_b32_e32 v1, 1, v9
	v_lshl_or_b32 v0, v1, 6, v0
	v_lshl_add_u32 v146, v11, 1, v0
	v_lshlrev_b32_e32 v0, 14, v12
	v_and_b32_e32 v0, 0xffff8000, v0
	s_waitcnt vmcnt(6)
	s_cmpk_lt_u32 s18, 0x100
	v_lshl_add_u32 v0, v13, 11, v0
	v_and_b32_e32 v1, 1, v12
	s_cselect_b64 s[16:17], -1, 0
	v_or_b32_e32 v162, 16, v139
	v_lshl_or_b32 v0, v1, 6, v0
	s_add_i32 s82, 0, 0x10000
	s_add_i32 s83, 0, 0x14000
	v_lshl_or_b32 v141, s19, 6, v139
	v_or_b32_e32 v142, v140, v139
	v_and_or_b32 v163, v8, 3, v145
	v_or_b32_e32 v144, v140, v162
	v_mov_b32_e32 v137, v131
	v_mov_b32_e32 v147, v131
	v_lshl_add_u32 v148, v14, 1, v0
	v_mov_b32_e32 v149, v131
	s_mov_b64 s[18:19], 64
	v_add_u32_e32 v164, s82, v143
	v_add_u32_e32 v165, s83, v143
	v_add_u32_e32 v166, 0, v3
	v_mov_b32_e32 v167, 0x3e38aa3b
	s_barrier
	s_waitcnt vmcnt(0)
	s_branch .LBB0_143

; #define PG8_STAGE(bufoff, gbase, voff) do { _Pragma("unroll") for (int _i = 0; _i < 2; ++_i) \
;         __builtin_amdgcn_global_load_lds((const unsigned*)((const char*)(gbase) + (voff)[_i]), (LAS unsigned*)(lds + (bufoff) + ldsw + _i * 8192), 16, 0, 0); } while (0)
; #define PG8_LDA(dst, b, h) do { _Pragma("unroll") for (int m = 0; m < 4; ++m) _Pragma("unroll") for (int k = 0; k < 2; ++k) dst[m][k] = *(const LAS bf16x8*)(lds + PG8_SA(b, h) + aoff + m * 2048 + k * 1024); } while (0)
; #define PG8_LDB(dst, b, h) do { _Pragma("unroll") for (int n = 0; n < 2; ++n) _Pragma("unroll") for (int k = 0; k < 2; ++k) dst[n][k] = *(const LAS bf16x8*)(lds + PG8_SB(b, h) + boff + n * 2048 + k * 1024); } while (0)
; #define PG8_MMA(ai, bj, At, Bt) do { __builtin_amdgcn_s_setprio(1); _Pragma("unroll") for (int m = 0; m < 4; ++m) _Pragma("unroll") for (int n = 0; n < 2; ++n) _Pragma("unroll") for (int k = 0; k < 2; ++k) \
;         acc[ai][bj][m][n] = __builtin_amdgcn_mfma_f32_16x16x32_bf16(Bt[n][k], At[m][k], acc[ai][bj][m][n], 0, 0, 0); __builtin_amdgcn_s_setprio(0); } while (0)
; #define PG8_WAIT_V(n) asm volatile("s_waitcnt vmcnt(" #n ")" ::: "memory")
; #define PG8_WAIT_L(n) asm volatile("s_waitcnt lgkmcnt(" #n ")" ::: "memory")
; #define PG8_BAR __builtin_amdgcn_s_barrier()
; template <class Epi, class Sched, bool ALIGN_EPI = false, bool SP2 = true>
; DI void gemm_phase(LAS unsigned char* lds, const Gemm g, const Sched& S, const Epi& E, f32x4 (&acc)[2][2][4][2]) {
;     ...
;         for (int t = 0; t < nt; t += 2) {
;             const bool last = (t == nt - 2);
;             const char* a1 = cA + (size_t)(t + 1) * kstep;
;             const char* a2 = last ? nA : cA + (size_t)(t + 2) * kstep; const char* b2 = last ? nB : cB + (size_t)(t + 2) * kstep;
;             const char* a3 = a2 + kstep; const char* b3 = b2 + kstep;
;             if constexpr (SP2) {
;             PG8_LDB(B0, 0, 0); PG8_LDB(B1, 0, 1); PG8_SCHED; PG8_LDA(At, 0, 0); PG8_STAGE(PG8_SA(1, 1), a1 + hstep, voffA);
;             PG8_WAIT_V(8); PG8_WAIT_L(0); PG8_BAR; PG8_MMA(0, 0, At, B0); PG8_MMA(0, 1, At, B1); PG8_BAR; PG8_SCHED;
;             PG8_LDA(At, 0, 1); PG8_STAGE(PG8_SB(0, 0), b2, voffB); PG8_STAGE(PG8_SB(0, 1), b2 + hstep, voffB); PG8_STAGE(PG8_SA(0, 0), a2, voffA);
;             PG8_WAIT_V(8); PG8_WAIT_L(0); PG8_BAR; PG8_MMA(1, 0, At, B0); PG8_MMA(1, 1, At, B1); PG8_BAR; PG8_SCHED;
.LBB0_159:
	ds_read_b128 v[150:153], v164
	ds_read_b128 v[154:157], v164 offset:1024
	ds_read_b128 v[158:161], v164 offset:2048
	ds_read_b128 v[168:171], v164 offset:3072
	ds_read_b128 v[172:175], v165
	ds_read_b128 v[180:183], v165 offset:1024
	ds_read_b128 v[184:187], v165 offset:2048
	ds_read_b128 v[188:191], v165 offset:3072
	s_add_u32 s30, s0, 0xfffc0080
	s_addc_u32 s31, s1, -1
	s_cmp_eq_u32 s62, 12
	s_cselect_b32 s35, s25, s31
	s_cselect_b32 s34, s52, s30
	s_cselect_b32 s31, s23, s55
	s_cselect_b32 s30, s53, s54
	v_lshl_add_u64 v[176:177], s[0:1], 0, v[146:147]
	s_add_i32 m0, s74, 0xc000
	ds_read_b128 v[192:195], v166
	ds_read_b128 v[196:199], v166 offset:1024
	ds_read_b128 v[202:205], v166 offset:2048
	ds_read_b128 v[206:209], v166 offset:3072
	ds_read_b128 v[210:213], v166 offset:4096
	ds_read_b128 v[214:217], v166 offset:5120
	ds_read_b128 v[218:221], v166 offset:6144
	ds_read_b128 v[222:225], v166 offset:7168
	global_load_lds_dwordx4 v[176:177], off
	v_lshl_add_u64 v[176:177], s[0:1], 0, v[148:149]
	s_add_i32 m0, s74, 0xe000
	s_nop 0
	global_load_lds_dwordx4 v[176:177], off
	s_waitcnt vmcnt(8)
	s_waitcnt lgkmcnt(0)
	s_barrier
	s_setprio 1
	s_waitcnt lgkmcnt(0)
	v_mfma_f32_16x16x32_bf16 v[124:127], v[150:153], v[192:195], v[124:127]
	v_mfma_f32_16x16x32_bf16 v[120:123], v[158:161], v[192:195], v[120:123]
	v_mfma_f32_16x16x32_bf16 v[108:111], v[150:153], v[202:205], v[108:111]
	v_mfma_f32_16x16x32_bf16 v[104:107], v[158:161], v[202:205], v[104:107]
	v_mfma_f32_16x16x32_bf16 v[92:95], v[150:153], v[210:213], v[92:95]
	v_mfma_f32_16x16x32_bf16 v[88:91], v[158:161], v[210:213], v[88:91]
	v_mfma_f32_16x16x32_bf16 v[76:79], v[150:153], v[218:221], v[76:79]
	v_mfma_f32_16x16x32_bf16 v[72:75], v[158:161], v[218:221], v[72:75]
	v_mfma_f32_16x16x32_bf16 v[124:127], v[154:157], v[196:199], v[124:127]
	v_mfma_f32_16x16x32_bf16 v[120:123], v[168:171], v[196:199], v[120:123]
	v_mfma_f32_16x16x32_bf16 v[108:111], v[154:157], v[206:209], v[108:111]
	v_mfma_f32_16x16x32_bf16 v[104:107], v[168:171], v[206:209], v[104:107]
	v_mfma_f32_16x16x32_bf16 v[92:95], v[154:157], v[214:217], v[92:95]
	v_mfma_f32_16x16x32_bf16 v[88:91], v[168:171], v[214:217], v[88:91]
	v_mfma_f32_16x16x32_bf16 v[76:79], v[154:157], v[222:225], v[76:79]
	v_mfma_f32_16x16x32_bf16 v[72:75], v[168:171], v[222:225], v[72:75]
	s_setprio 0
	s_setprio 1
	v_mfma_f32_16x16x32_bf16 v[116:119], v[172:175], v[192:195], v[116:119]
	v_mfma_f32_16x16x32_bf16 v[112:115], v[184:187], v[192:195], v[112:115]
	v_mfma_f32_16x16x32_bf16 v[100:103], v[172:175], v[202:205], v[100:103]
	v_mfma_f32_16x16x32_bf16 v[96:99], v[184:187], v[202:205], v[96:99]
	v_mfma_f32_16x16x32_bf16 v[84:87], v[172:175], v[210:213], v[84:87]
	v_mfma_f32_16x16x32_bf16 v[80:83], v[184:187], v[210:213], v[80:83]
	v_mfma_f32_16x16x32_bf16 v[68:71], v[172:175], v[218:221], v[68:71]
	v_mfma_f32_16x16x32_bf16 v[64:67], v[184:187], v[218:221], v[64:67]
	v_mfma_f32_16x16x32_bf16 v[116:119], v[180:183], v[196:199], v[116:119]
	v_mfma_f32_16x16x32_bf16 v[112:115], v[188:191], v[196:199], v[112:115]
	v_mfma_f32_16x16x32_bf16 v[100:103], v[180:183], v[206:209], v[100:103]
	v_mfma_f32_16x16x32_bf16 v[96:99], v[188:191], v[206:209], v[96:99]
	v_mfma_f32_16x16x32_bf16 v[84:87], v[180:183], v[214:217], v[84:87]
	v_mfma_f32_16x16x32_bf16 v[80:83], v[188:191], v[214:217], v[80:83]
	v_mfma_f32_16x16x32_bf16 v[68:71], v[180:183], v[222:225], v[68:71]
	v_mfma_f32_16x16x32_bf16 v[64:67], v[188:191], v[222:225], v[64:67]
	s_setprio 0
	s_barrier
	s_add_i32 s63, s82, s39
	v_lshl_add_u64 v[176:177], s[30:31], 0, v[130:131]
	s_mov_b32 m0, s63
	ds_read_b128 v[192:195], v166 offset:16384
	ds_read_b128 v[196:199], v166 offset:17408
	ds_read_b128 v[202:205], v166 offset:18432
	ds_read_b128 v[206:209], v166 offset:19456
	ds_read_b128 v[210:213], v166 offset:20480
	ds_read_b128 v[214:217], v166 offset:21504
	ds_read_b128 v[218:221], v166 offset:22528
	ds_read_b128 v[222:225], v166 offset:23552
	global_load_lds_dwordx4 v[176:177], off
	s_add_i32 m0, s63, 0x2000
	s_add_u32 s72, s30, 0x10000
	v_lshl_add_u64 v[226:227], s[30:31], 0, v[134:135]
	s_addc_u32 s73, s31, 0
	s_add_i32 s63, s83, s39
	global_load_lds_dwordx4 v[226:227], off
	v_lshl_add_u64 v[228:229], s[72:73], 0, v[130:131]
	s_mov_b32 m0, s63
	v_lshl_add_u64 v[230:231], s[34:35], 0, v[132:133]
	global_load_lds_dwordx4 v[228:229], off
	v_lshl_add_u64 v[228:229], s[72:73], 0, v[134:135]
	s_add_i32 m0, s63, 0x2000
	s_nop 0
	global_load_lds_dwordx4 v[228:229], off
	v_lshl_add_u64 v[228:229], s[34:35], 0, v[128:129]
	s_mov_b32 m0, s74
	s_nop 0
	global_load_lds_dwordx4 v[228:229], off
	s_mov_b32 m0, s75
	s_nop 0
	global_load_lds_dwordx4 v[230:231], off
	s_waitcnt vmcnt(8)
	s_waitcnt lgkmcnt(0)
	s_barrier
; #define PG8_STAGE(bufoff, gbase, voff) do { _Pragma("unroll") for (int _i = 0; _i < 2; ++_i) \
;         __builtin_amdgcn_global_load_lds((const unsigned*)((const char*)(gbase) + (voff)[_i]), (LAS unsigned*)(lds + (bufoff) + ldsw + _i * 8192), 16, 0, 0); } while (0)
; #define PG8_LDA(dst, b, h) do { _Pragma("unroll") for (int m = 0; m < 4; ++m) _Pragma("unroll") for (int k = 0; k < 2; ++k) dst[m][k] = *(const LAS bf16x8*)(lds + PG8_SA(b, h) + aoff + m * 2048 + k * 1024); } while (0)
; #define PG8_LDB(dst, b, h) do { _Pragma("unroll") for (int n = 0; n < 2; ++n) _Pragma("unroll") for (int k = 0; k < 2; ++k) dst[n][k] = *(const LAS bf16x8*)(lds + PG8_SB(b, h) + boff + n * 2048 + k * 1024); } while (0)
; #define PG8_MMA(ai, bj, At, Bt) do { __builtin_amdgcn_s_setprio(1); _Pragma("unroll") for (int m = 0; m < 4; ++m) _Pragma("unroll") for (int n = 0; n < 2; ++n) _Pragma("unroll") for (int k = 0; k < 2; ++k) \
;         acc[ai][bj][m][n] = __builtin_amdgcn_mfma_f32_16x16x32_bf16(Bt[n][k], At[m][k], acc[ai][bj][m][n], 0, 0, 0); __builtin_amdgcn_s_setprio(0); } while (0)
; #define PG8_WAIT_V(n) asm volatile("s_waitcnt vmcnt(" #n ")" ::: "memory")
; #define PG8_WAIT_L(n) asm volatile("s_waitcnt lgkmcnt(" #n ")" ::: "memory")
; #define PG8_BAR __builtin_amdgcn_s_barrier()
; #define PG8_SCHED __builtin_amdgcn_sched_barrier(0)
; template <class Epi, class Sched, bool ALIGN_EPI = false, bool SP2 = true>
; DI void gemm_phase(LAS unsigned char* lds, const Gemm g, const Sched& S, const Epi& E, f32x4 (&acc)[2][2][4][2]) {
;     ...
;             PG8_WAIT_V(8); PG8_WAIT_L(0); PG8_BAR; PG8_MMA(1, 0, At, B0); PG8_MMA(1, 1, At, B1); PG8_BAR; PG8_SCHED;
;             PG8_LDB(B0, 1, 0); PG8_LDB(B1, 1, 1); PG8_SCHED; PG8_LDA(At, 1, 0); PG8_STAGE(PG8_SA(0, 1), a2 + hstep, voffA);
;             PG8_WAIT_V(8); PG8_WAIT_L(0); PG8_BAR; PG8_MMA(0, 0, At, B0); PG8_MMA(0, 1, At, B1); PG8_BAR; PG8_SCHED;
;             PG8_LDA(At, 1, 1); PG8_STAGE(PG8_SB(1, 0), b3, voffB); PG8_STAGE(PG8_SB(1, 1), b3 + hstep, voffB); PG8_STAGE(PG8_SA(1, 0), a3, voffA);
	s_setprio 1
	s_waitcnt lgkmcnt(0)
	v_mfma_f32_16x16x32_bf16 v[60:63], v[150:153], v[192:195], v[60:63]
	v_mfma_f32_16x16x32_bf16 v[56:59], v[158:161], v[192:195], v[56:59]
	v_mfma_f32_16x16x32_bf16 v[44:47], v[150:153], v[202:205], v[44:47]
	v_mfma_f32_16x16x32_bf16 v[40:43], v[158:161], v[202:205], v[40:43]
	v_mfma_f32_16x16x32_bf16 v[28:31], v[150:153], v[210:213], v[28:31]
	v_mfma_f32_16x16x32_bf16 v[24:27], v[158:161], v[210:213], v[24:27]
	v_mfma_f32_16x16x32_bf16 v[12:15], v[150:153], v[218:221], v[12:15]
	v_mfma_f32_16x16x32_bf16 v[8:11], v[158:161], v[218:221], v[8:11]
	v_mfma_f32_16x16x32_bf16 v[60:63], v[154:157], v[196:199], v[60:63]
	v_mfma_f32_16x16x32_bf16 v[56:59], v[168:171], v[196:199], v[56:59]
	v_mfma_f32_16x16x32_bf16 v[44:47], v[154:157], v[206:209], v[44:47]
	v_mfma_f32_16x16x32_bf16 v[40:43], v[168:171], v[206:209], v[40:43]
	v_mfma_f32_16x16x32_bf16 v[28:31], v[154:157], v[214:217], v[28:31]
	v_mfma_f32_16x16x32_bf16 v[24:27], v[168:171], v[214:217], v[24:27]
	v_mfma_f32_16x16x32_bf16 v[12:15], v[154:157], v[222:225], v[12:15]
	v_mfma_f32_16x16x32_bf16 v[8:11], v[168:171], v[222:225], v[8:11]
	s_setprio 0
	s_setprio 1
	v_mfma_f32_16x16x32_bf16 v[52:55], v[172:175], v[192:195], v[52:55]
	v_mfma_f32_16x16x32_bf16 v[48:51], v[184:187], v[192:195], v[48:51]
	v_mfma_f32_16x16x32_bf16 v[36:39], v[172:175], v[202:205], v[36:39]
	v_mfma_f32_16x16x32_bf16 v[32:35], v[184:187], v[202:205], v[32:35]
	v_mfma_f32_16x16x32_bf16 v[20:23], v[172:175], v[210:213], v[20:23]
	v_mfma_f32_16x16x32_bf16 v[16:19], v[184:187], v[210:213], v[16:19]
	v_mfma_f32_16x16x32_bf16 v[4:7], v[172:175], v[218:221], v[4:7]
	v_mfma_f32_16x16x32_bf16 v[0:3], v[184:187], v[218:221], v[0:3]
	v_mfma_f32_16x16x32_bf16 v[52:55], v[180:183], v[196:199], v[52:55]
	v_mfma_f32_16x16x32_bf16 v[48:51], v[188:191], v[196:199], v[48:51]
	v_mfma_f32_16x16x32_bf16 v[36:39], v[180:183], v[206:209], v[36:39]
	v_mfma_f32_16x16x32_bf16 v[32:35], v[188:191], v[206:209], v[32:35]
	v_mfma_f32_16x16x32_bf16 v[20:23], v[180:183], v[214:217], v[20:23]
	v_mfma_f32_16x16x32_bf16 v[16:19], v[188:191], v[214:217], v[16:19]
	v_mfma_f32_16x16x32_bf16 v[4:7], v[180:183], v[222:225], v[4:7]
	v_mfma_f32_16x16x32_bf16 v[0:3], v[188:191], v[222:225], v[0:3]
	s_setprio 0
	s_barrier
	s_add_i32 s63, 0, 0x18000
	s_add_i32 s64, 0, 0x1c000
	v_add_u32_e32 v168, s63, v143
	v_add_u32_e32 v178, s64, v143
	ds_read_b128 v[150:153], v168
	ds_read_b128 v[154:157], v168 offset:1024
	ds_read_b128 v[158:161], v168 offset:2048
	ds_read_b128 v[168:171], v168 offset:3072
	ds_read_b128 v[172:175], v178
	ds_read_b128 v[180:183], v178 offset:1024
	ds_read_b128 v[184:187], v178 offset:2048
	ds_read_b128 v[188:191], v178 offset:3072
	s_add_u32 s34, s34, 0x40000
	s_addc_u32 s35, s35, 0
	s_mov_b32 m0, s76
	v_lshl_add_u64 v[232:233], s[34:35], 0, v[128:129]
	ds_read_b128 v[192:195], v166 offset:32768
	ds_read_b128 v[196:199], v166 offset:33792
	ds_read_b128 v[202:205], v166 offset:34816
	ds_read_b128 v[206:209], v166 offset:35840
	ds_read_b128 v[210:213], v166 offset:36864
	ds_read_b128 v[214:217], v166 offset:37888
	ds_read_b128 v[218:221], v166 offset:38912
	ds_read_b128 v[222:225], v166 offset:39936
	global_load_lds_dwordx4 v[232:233], off
	v_lshl_add_u64 v[232:233], s[34:35], 0, v[132:133]
	s_mov_b32 m0, s77
	s_nop 0
	global_load_lds_dwordx4 v[232:233], off
	s_waitcnt vmcnt(8)
	s_waitcnt lgkmcnt(0)
	s_barrier
	s_setprio 1
	s_waitcnt lgkmcnt(0)
	v_mfma_f32_16x16x32_bf16 v[124:127], v[150:153], v[192:195], v[124:127]
	v_mfma_f32_16x16x32_bf16 v[120:123], v[158:161], v[192:195], v[120:123]
	v_mfma_f32_16x16x32_bf16 v[108:111], v[150:153], v[202:205], v[108:111]
	v_mfma_f32_16x16x32_bf16 v[104:107], v[158:161], v[202:205], v[104:107]
	v_mfma_f32_16x16x32_bf16 v[92:95], v[150:153], v[210:213], v[92:95]
	v_mfma_f32_16x16x32_bf16 v[88:91], v[158:161], v[210:213], v[88:91]
	v_mfma_f32_16x16x32_bf16 v[76:79], v[150:153], v[218:221], v[76:79]
	v_mfma_f32_16x16x32_bf16 v[72:75], v[158:161], v[218:221], v[72:75]
	v_mfma_f32_16x16x32_bf16 v[124:127], v[154:157], v[196:199], v[124:127]
	v_mfma_f32_16x16x32_bf16 v[120:123], v[168:171], v[196:199], v[120:123]
	v_mfma_f32_16x16x32_bf16 v[108:111], v[154:157], v[206:209], v[108:111]
	v_mfma_f32_16x16x32_bf16 v[104:107], v[168:171], v[206:209], v[104:107]
	v_mfma_f32_16x16x32_bf16 v[92:95], v[154:157], v[214:217], v[92:95]
	v_mfma_f32_16x16x32_bf16 v[88:91], v[168:171], v[214:217], v[88:91]
	v_mfma_f32_16x16x32_bf16 v[76:79], v[154:157], v[222:225], v[76:79]
	v_mfma_f32_16x16x32_bf16 v[72:75], v[168:171], v[222:225], v[72:75]
	s_setprio 0
	s_setprio 1
	v_mfma_f32_16x16x32_bf16 v[116:119], v[172:175], v[192:195], v[116:119]
	v_mfma_f32_16x16x32_bf16 v[112:115], v[184:187], v[192:195], v[112:115]
	v_mfma_f32_16x16x32_bf16 v[100:103], v[172:175], v[202:205], v[100:103]
	v_mfma_f32_16x16x32_bf16 v[96:99], v[184:187], v[202:205], v[96:99]
	v_mfma_f32_16x16x32_bf16 v[84:87], v[172:175], v[210:213], v[84:87]
	v_mfma_f32_16x16x32_bf16 v[80:83], v[184:187], v[210:213], v[80:83]
	v_mfma_f32_16x16x32_bf16 v[68:71], v[172:175], v[218:221], v[68:71]
	v_mfma_f32_16x16x32_bf16 v[64:67], v[184:187], v[218:221], v[64:67]
	v_mfma_f32_16x16x32_bf16 v[116:119], v[180:183], v[196:199], v[116:119]
	v_mfma_f32_16x16x32_bf16 v[112:115], v[188:191], v[196:199], v[112:115]
	v_mfma_f32_16x16x32_bf16 v[100:103], v[180:183], v[206:209], v[100:103]
	v_mfma_f32_16x16x32_bf16 v[96:99], v[188:191], v[206:209], v[96:99]
	v_mfma_f32_16x16x32_bf16 v[84:87], v[180:183], v[214:217], v[84:87]
	v_mfma_f32_16x16x32_bf16 v[80:83], v[188:191], v[214:217], v[80:83]
	v_mfma_f32_16x16x32_bf16 v[68:71], v[180:183], v[222:225], v[68:71]
	v_mfma_f32_16x16x32_bf16 v[64:67], v[188:191], v[222:225], v[64:67]
	s_setprio 0
	s_barrier
; #define PG8_STAGE(bufoff, gbase, voff) do { _Pragma("unroll") for (int _i = 0; _i < 2; ++_i) \
;         __builtin_amdgcn_global_load_lds((const unsigned*)((const char*)(gbase) + (voff)[_i]), (LAS unsigned*)(lds + (bufoff) + ldsw + _i * 8192), 16, 0, 0); } while (0)
; #define PG8_LDA(dst, b, h) do { _Pragma("unroll") for (int m = 0; m < 4; ++m) _Pragma("unroll") for (int k = 0; k < 2; ++k) dst[m][k] = *(const LAS bf16x8*)(lds + PG8_SA(b, h) + aoff + m * 2048 + k * 1024); } while (0)
; #define PG8_MMA(ai, bj, At, Bt) do { __builtin_amdgcn_s_setprio(1); _Pragma("unroll") for (int m = 0; m < 4; ++m) _Pragma("unroll") for (int n = 0; n < 2; ++n) _Pragma("unroll") for (int k = 0; k < 2; ++k) \
;         acc[ai][bj][m][n] = __builtin_amdgcn_mfma_f32_16x16x32_bf16(Bt[n][k], At[m][k], acc[ai][bj][m][n], 0, 0, 0); __builtin_amdgcn_s_setprio(0); } while (0)
; #define PG8_WAIT_V(n) asm volatile("s_waitcnt vmcnt(" #n ")" ::: "memory")
; #define PG8_WAIT_L(n) asm volatile("s_waitcnt lgkmcnt(" #n ")" ::: "memory")
; #define PG8_BAR __builtin_amdgcn_s_barrier()
; #define PG8_SCHED __builtin_amdgcn_sched_barrier(0)
; template <class Epi, class Sched, bool ALIGN_EPI = false, bool SP2 = true>
; DI void gemm_phase(LAS unsigned char* lds, const Gemm g, const Sched& S, const Epi& E, f32x4 (&acc)[2][2][4][2]) {
;     ...
;         for (int t = 0; t < nt; t += 2) {
;     ...
;             PG8_WAIT_V(8); PG8_WAIT_L(0); PG8_BAR; PG8_MMA(0, 0, At, B0); PG8_MMA(0, 1, At, B1); PG8_BAR; PG8_SCHED;
;             PG8_LDA(At, 1, 1); PG8_STAGE(PG8_SB(1, 0), b3, voffB); PG8_STAGE(PG8_SB(1, 1), b3 + hstep, voffB); PG8_STAGE(PG8_SA(1, 0), a3, voffA);
;             PG8_WAIT_V(8); PG8_WAIT_L(0); PG8_BAR; PG8_MMA(1, 0, At, B0); PG8_MMA(1, 1, At, B1); PG8_BAR; PG8_SCHED;
	s_add_i32 s34, s63, s39
	v_lshl_add_u64 v[176:177], v[176:177], 0, s[14:15]
	s_mov_b32 m0, s34
	ds_read_b128 v[192:195], v166 offset:49152
	ds_read_b128 v[196:199], v166 offset:50176
	ds_read_b128 v[202:205], v166 offset:51200
	ds_read_b128 v[206:209], v166 offset:52224
	ds_read_b128 v[210:213], v166 offset:53248
	ds_read_b128 v[214:217], v166 offset:54272
	ds_read_b128 v[218:221], v166 offset:55296
	ds_read_b128 v[222:225], v166 offset:56320
	global_load_lds_dwordx4 v[176:177], off
	s_add_i32 m0, s34, 0x2000
	s_add_u32 s30, s30, 0x10080
	v_lshl_add_u64 v[176:177], v[226:227], 0, s[14:15]
	s_addc_u32 s31, s31, 0
	s_add_i32 s34, s64, s39
	global_load_lds_dwordx4 v[176:177], off
	v_lshl_add_u64 v[176:177], s[30:31], 0, v[130:131]
	s_mov_b32 m0, s34
	s_nop 0
	global_load_lds_dwordx4 v[176:177], off
	v_lshl_add_u64 v[176:177], s[30:31], 0, v[134:135]
	s_add_i32 m0, s34, 0x2000
	s_nop 0
	global_load_lds_dwordx4 v[176:177], off
	v_lshl_add_u64 v[176:177], v[228:229], 0, s[14:15]
	s_mov_b32 m0, s80
	s_nop 0
	global_load_lds_dwordx4 v[176:177], off
	v_lshl_add_u64 v[176:177], v[230:231], 0, s[14:15]
	s_mov_b32 m0, s81
	s_nop 0
	global_load_lds_dwordx4 v[176:177], off
	s_waitcnt vmcnt(8)
	s_waitcnt lgkmcnt(0)
	s_barrier
	s_setprio 1
	s_waitcnt lgkmcnt(0)
	v_mfma_f32_16x16x32_bf16 v[60:63], v[150:153], v[192:195], v[60:63]
	v_mfma_f32_16x16x32_bf16 v[56:59], v[158:161], v[192:195], v[56:59]
	v_mfma_f32_16x16x32_bf16 v[44:47], v[150:153], v[202:205], v[44:47]
	v_mfma_f32_16x16x32_bf16 v[40:43], v[158:161], v[202:205], v[40:43]
	v_mfma_f32_16x16x32_bf16 v[28:31], v[150:153], v[210:213], v[28:31]
	v_mfma_f32_16x16x32_bf16 v[24:27], v[158:161], v[210:213], v[24:27]
	v_mfma_f32_16x16x32_bf16 v[12:15], v[150:153], v[218:221], v[12:15]
	v_mfma_f32_16x16x32_bf16 v[8:11], v[158:161], v[218:221], v[8:11]
	v_mfma_f32_16x16x32_bf16 v[60:63], v[154:157], v[196:199], v[60:63]
	v_mfma_f32_16x16x32_bf16 v[56:59], v[168:171], v[196:199], v[56:59]
	v_mfma_f32_16x16x32_bf16 v[44:47], v[154:157], v[206:209], v[44:47]
	v_mfma_f32_16x16x32_bf16 v[40:43], v[168:171], v[206:209], v[40:43]
	v_mfma_f32_16x16x32_bf16 v[28:31], v[154:157], v[214:217], v[28:31]
	v_mfma_f32_16x16x32_bf16 v[24:27], v[168:171], v[214:217], v[24:27]
	v_mfma_f32_16x16x32_bf16 v[12:15], v[154:157], v[222:225], v[12:15]
	v_mfma_f32_16x16x32_bf16 v[8:11], v[168:171], v[222:225], v[8:11]
	s_setprio 0
	s_setprio 1
	v_mfma_f32_16x16x32_bf16 v[52:55], v[172:175], v[192:195], v[52:55]
	v_mfma_f32_16x16x32_bf16 v[48:51], v[184:187], v[192:195], v[48:51]
	v_mfma_f32_16x16x32_bf16 v[36:39], v[172:175], v[202:205], v[36:39]
	v_mfma_f32_16x16x32_bf16 v[32:35], v[184:187], v[202:205], v[32:35]
	v_mfma_f32_16x16x32_bf16 v[20:23], v[172:175], v[210:213], v[20:23]
	v_mfma_f32_16x16x32_bf16 v[16:19], v[184:187], v[210:213], v[16:19]
	v_mfma_f32_16x16x32_bf16 v[4:7], v[172:175], v[218:221], v[4:7]
	v_mfma_f32_16x16x32_bf16 v[0:3], v[184:187], v[218:221], v[0:3]
	v_mfma_f32_16x16x32_bf16 v[52:55], v[180:183], v[196:199], v[52:55]
	v_mfma_f32_16x16x32_bf16 v[48:51], v[188:191], v[196:199], v[48:51]
	v_mfma_f32_16x16x32_bf16 v[36:39], v[180:183], v[206:209], v[36:39]
	v_mfma_f32_16x16x32_bf16 v[32:35], v[188:191], v[206:209], v[32:35]
	v_mfma_f32_16x16x32_bf16 v[20:23], v[180:183], v[214:217], v[20:23]
	v_mfma_f32_16x16x32_bf16 v[16:19], v[188:191], v[214:217], v[16:19]
	v_mfma_f32_16x16x32_bf16 v[4:7], v[180:183], v[222:225], v[4:7]
	v_mfma_f32_16x16x32_bf16 v[0:3], v[188:191], v[222:225], v[0:3]
	s_setprio 0
	s_barrier
	s_add_i32 s62, s62, 2
	s_add_u32 s0, s0, 0x100
	s_addc_u32 s1, s1, 0
	s_add_u32 s54, s54, 0x100
	s_addc_u32 s55, s55, 0
	s_cmp_gt_u32 s62, 13
	s_cbranch_scc0 .LBB0_159
	s_and_b64 vcc, exec, s[16:17]
	s_cbranch_vccz .LBB0_162
	s_barrier

;     DI void operator()(const f32x4 (&acc)[2][2][4][2], const Unit& u, int wr, int wc, int fr, int fq) const {
;         bf16_t* base; int ldc;
;         if (u.kind == 0) { base = qk; ldc = 1024; }
;         else if (u.kind == 1) { base = vt; ldc = T; }
;         else if (u.kind == 2) { base = r; ldc = 2048; }
;         else if (u.kind == 3) { base = mk; ldc = 256; }
;         else { base = mvt; ldc = 256; }
;         const float sc = ((u.kind == 0 && u.on < 2) || (u.kind == 2 && u.on == 3)) ? QSCALE : 1.0f;
;         const int row0 = u.om * BM + wr * 64 + fr, col0 = u.on * BM + wc * 32 + 8 * fq;
.LBB0_177:
	s_lshl_b32 s0, s37, 8
	v_lshl_add_u32 v168, s36, 8, v141
	s_lshl_b32 s36, s79, 1
	s_or_b32 s36, s0, s36
	s_ashr_i32 s34, s37, 1
	s_cmp_lt_u32 s37, 2
	s_cselect_b64 s[0:1], -1, 0
	s_ashr_i32 s35, s34, 31
	s_lshl_b64 s[34:35], s[34:35], 24
	v_ashrrev_i32_e32 v150, 6, v168
	s_add_u32 s34, s30, s34
	v_ashrrev_i32_e32 v151, 31, v150
	s_addc_u32 s35, s31, s35
	v_lshlrev_b64 v[154:155], 2, v[150:151]
	v_or_b32_e32 v154, v154, v138
	s_mov_b64 s[72:73], -1
	s_mov_b64 s[54:55], 0
	s_cmp_lt_i32 s38, 1
	s_mov_b64 s[62:63], 0
	s_cbranch_scc1 .LBB0_181
	s_cmp_eq_u32 s38, 1
	s_mov_b64 s[62:63], -1
	s_cbranch_scc0 .LBB0_180
	s_ashr_i32 s62, s36, 5
	s_ashr_i32 s63, s62, 31
	s_lshl_b64 s[62:63], s[62:63], 11
	v_lshlrev_b64 v[150:151], 6, v[154:155]
	v_lshl_add_u64 v[150:151], v[150:151], 0, s[62:63]
	v_or_b32_e32 v150, v150, v142
	v_lshl_add_u64 v[160:161], v[150:151], 4, s[30:31]
	s_mov_b64 s[62:63], 0

; DI unsigned pk_bf16(float lo, float hi) { f32x2 v = {lo, hi}; bf2_t b = __builtin_convertvector(v, bf2_t); return __builtin_bit_cast(unsigned, b); }
; DI int pi32e(int r) { return (r & ~12) | ((r & 4) << 1) | ((r & 8) >> 1); }
;     DI void operator()(const f32x4 (&acc)[2][2][4][2], const Unit& u, int wr, int wc, int fr, int fq) const {
;     ...
;         const int row0 = u.om * BM + wr * 64 + fr, col0 = u.on * BM + wc * 32 + 8 * fq;
; #pragma unroll
;         for (int ai = 0; ai < 2; ++ai)
; #pragma unroll
;             for (int m = 0; m < 4; ++m) { const int row = row0 + ai * HALF + m * 16;
; #pragma unroll
;                 for (int bj = 0; bj < 2; ++bj) { const f32x4 v0 = acc[ai][bj][m][0] * sc, v1 = acc[ai][bj][m][1] * sc; const int col = col0 + bj * HALF;
;                     u32x4 w; w.x = pk_bf16(v0[0], v0[1]); w.y = pk_bf16(v0[2], v0[3]); w.z = pk_bf16(v1[0], v1[1]); w.w = pk_bf16(v1[2], v1[3]);
;                     bf16_t* dst;
;                     if (u.kind == 0) {
;                         const int isk = col >> 9, c = col & 511, rr = isk ? pi32e(row & 31) : (row & 31);
;                         dst = base + (size_t)isk * ((size_t)T * 512) + ((((size_t)(row >> 5) * 8 + (c >> 6)) * 4 + ((c & 63) >> 4)) * 64 + ((c >> 3) & 1) * 32 + rr) * 8;
;                     } else if (u.kind == 1) {
;                         dst = base + ((((size_t)(col >> 5) * 8 + (row >> 6)) * 4 + ((row & 63) >> 5) * 2 + ((col & 31) >> 4)) * 64 + ((col >> 3) & 1) * 32 + (row & 31)) * 8;
;                     } else dst = base + (size_t)row * ldc + col;
;                     *(u32x4*)dst = w; } }
.LBB0_185:
	v_ashrrev_i32_e32 v150, 5, v168
	v_ashrrev_i32_e32 v151, 31, v150
	v_lshlrev_b64 v[156:157], 5, v[150:151]
	s_andn2_b64 vcc, exec, s[54:55]
	v_cndmask_b32_e64 v170, v163, v139, s[0:1]
	v_bfe_u32 v169, v152, 4, 2
	s_cbranch_vccnz .LBB0_187
	s_lshr_b32 s23, s36, 4
	s_and_b32 s23, s23, 28
	v_or3_b32 v150, v169, s23, v156
	v_mov_b32_e32 v151, v157
	v_lshlrev_b64 v[150:151], 6, v[150:151]
	v_or_b32_e32 v150, v150, v170
	v_or_b32_e32 v150, v150, v140
	v_lshl_add_u64 v[160:161], v[150:151], 4, s[34:35]
.LBB0_187:
	s_cmp_eq_u32 s38, 0
	s_cselect_b64 s[54:55], -1, 0
	s_cmp_lt_i32 s37, 2
	s_cselect_b64 s[62:63], -1, 0
	s_and_b64 s[54:55], s[54:55], s[62:63]
	s_cmp_eq_u32 s38, 2
	s_cselect_b64 s[62:63], -1, 0
	s_cmp_eq_u32 s37, 3
	s_cselect_b64 s[72:73], -1, 0
	s_and_b64 s[62:63], s[62:63], s[72:73]
	s_or_b64 vcc, s[54:55], s[62:63]
	v_cndmask_b32_e32 v150, 1.0, v167, vcc
	v_mov_b32_e32 v151, v150
	v_pk_mul_f32 v[126:127], v[150:151], v[126:127] op_sel_hi:[0,1]
	v_pk_mul_f32 v[124:125], v[150:151], v[124:125] op_sel_hi:[0,1]
	v_pk_mul_f32 v[172:173], v[150:151], v[122:123] op_sel_hi:[0,1]
	v_pk_mul_f32 v[122:123], v[150:151], v[120:121] op_sel_hi:[0,1]
	s_or_b32 s23, s36, 32
	v_cvt_pk_bf16_f32 v120, v124, v125
	v_cvt_pk_bf16_f32 v121, v126, v127
	v_cvt_pk_bf16_f32 v122, v122, v123
	v_cvt_pk_bf16_f32 v123, v172, v173
	s_mov_b64 s[72:73], -1
	s_mov_b64 s[54:55], 0
	s_cmp_lt_i32 s38, 1
	s_mov_b64 s[62:63], 0
	global_store_dwordx4 v[160:161], v[120:123], off
	s_cbranch_scc0 .LBB0_300
	s_and_b64 vcc, exec, s[72:73]
	s_cbranch_vccnz .LBB0_303

; DI int pi32e(int r) { return (r & ~12) | ((r & 4) << 1) | ((r & 8) >> 1); }
;     DI void operator()(const f32x4 (&acc)[2][2][4][2], const Unit& u, int wr, int wc, int fr, int fq) const {
;     ...
;                     if (u.kind == 0) {
;                         const int isk = col >> 9, c = col & 511, rr = isk ? pi32e(row & 31) : (row & 31);
;                         dst = base + (size_t)isk * ((size_t)T * 512) + ((((size_t)(row >> 5) * 8 + (c >> 6)) * 4 + ((c & 63) >> 4)) * 64 + ((c >> 3) & 1) * 32 + rr) * 8;
;                     } else if (u.kind == 1) {
;                         dst = base + ((((size_t)(col >> 5) * 8 + (row >> 6)) * 4 + ((row & 63) >> 5) * 2 + ((col & 31) >> 4)) * 64 + ((col >> 3) & 1) * 32 + (row & 31)) * 8;
.LBB0_200:
	v_and_or_b32 v116, v116, 19, v145
	s_andn2_b64 vcc, exec, s[54:55]
	v_cndmask_b32_e64 v116, v116, v162, s[0:1]
	s_cbranch_vccnz .LBB0_202
	s_lshr_b32 s25, s36, 4
	s_and_b32 s25, s25, 28
	v_or3_b32 v114, v169, s25, v156
	v_mov_b32_e32 v115, v157
	v_lshlrev_b64 v[114:115], 6, v[114:115]
	v_or_b32_e32 v114, v114, v116
	v_or_b32_e32 v114, v114, v140
	v_lshl_add_u64 v[114:115], v[114:115], 4, s[34:35]

; DI int pi32e(int r) { return (r & ~12) | ((r & 4) << 1) | ((r & 8) >> 1); }
;     DI void operator()(const f32x4 (&acc)[2][2][4][2], const Unit& u, int wr, int wc, int fr, int fq) const {
;     ...
;                     if (u.kind == 0) {
;                         const int isk = col >> 9, c = col & 511, rr = isk ? pi32e(row & 31) : (row & 31);
;                         dst = base + (size_t)isk * ((size_t)T * 512) + ((((size_t)(row >> 5) * 8 + (c >> 6)) * 4 + ((c & 63) >> 4)) * 64 + ((c >> 3) & 1) * 32 + rr) * 8;
;                     } else if (u.kind == 1) {
;                         dst = base + ((((size_t)(col >> 5) * 8 + (row >> 6)) * 4 + ((row & 63) >> 5) * 2 + ((col & 31) >> 4)) * 64 + ((col >> 3) & 1) * 32 + (row & 31)) * 8;
.LBB0_215:
	v_ashrrev_i32_e32 v98, 5, v98
	v_ashrrev_i32_e32 v99, 31, v98
	s_andn2_b64 vcc, exec, s[54:55]
	v_lshlrev_b64 v[98:99], 5, v[98:99]
	s_cbranch_vccnz .LBB0_217
	s_lshr_b32 s25, s36, 4
	s_and_b32 s25, s25, 28
	v_or3_b32 v100, v169, s25, v98
	v_mov_b32_e32 v101, v99
	v_lshlrev_b64 v[100:101], 6, v[100:101]
	v_or_b32_e32 v100, v100, v170
	v_or_b32_e32 v100, v100, v140
	v_lshl_add_u64 v[100:101], v[100:101], 4, s[34:35]

; DI int pi32e(int r) { return (r & ~12) | ((r & 4) << 1) | ((r & 8) >> 1); }
;     DI void operator()(const f32x4 (&acc)[2][2][4][2], const Unit& u, int wr, int wc, int fr, int fq) const {
;     ...
;                     if (u.kind == 0) {
;                         const int isk = col >> 9, c = col & 511, rr = isk ? pi32e(row & 31) : (row & 31);
;                         dst = base + (size_t)isk * ((size_t)T * 512) + ((((size_t)(row >> 5) * 8 + (c >> 6)) * 4 + ((c & 63) >> 4)) * 64 + ((c >> 3) & 1) * 32 + rr) * 8;
;                     } else if (u.kind == 1) {
;                         dst = base + ((((size_t)(col >> 5) * 8 + (row >> 6)) * 4 + ((row & 63) >> 5) * 2 + ((col & 31) >> 4)) * 64 + ((col >> 3) & 1) * 32 + (row & 31)) * 8;
.LBB0_230:
	v_and_or_b32 v86, v80, 19, v145
	v_ashrrev_i32_e32 v80, 5, v80
	v_ashrrev_i32_e32 v81, 31, v80
	v_lshlrev_b64 v[80:81], 5, v[80:81]
	s_andn2_b64 vcc, exec, s[54:55]
	v_cndmask_b32_e64 v86, v86, v162, s[0:1]
	s_cbranch_vccnz .LBB0_232
	s_lshr_b32 s25, s36, 4
	s_and_b32 s25, s25, 28
	v_or3_b32 v84, v169, s25, v80
	v_mov_b32_e32 v85, v81
	v_lshlrev_b64 v[84:85], 6, v[84:85]
	v_or_b32_e32 v84, v84, v86
	v_or_b32_e32 v84, v84, v140
	v_lshl_add_u64 v[84:85], v[84:85], 4, s[34:35]

; DI int pi32e(int r) { return (r & ~12) | ((r & 4) << 1) | ((r & 8) >> 1); }
;     DI void operator()(const f32x4 (&acc)[2][2][4][2], const Unit& u, int wr, int wc, int fr, int fq) const {
;     ...
;                     if (u.kind == 0) {
;                         const int isk = col >> 9, c = col & 511, rr = isk ? pi32e(row & 31) : (row & 31);
;                         dst = base + (size_t)isk * ((size_t)T * 512) + ((((size_t)(row >> 5) * 8 + (c >> 6)) * 4 + ((c & 63) >> 4)) * 64 + ((c >> 3) & 1) * 32 + rr) * 8;
;                     } else if (u.kind == 1) {
;                         dst = base + ((((size_t)(col >> 5) * 8 + (row >> 6)) * 4 + ((row & 63) >> 5) * 2 + ((col & 31) >> 4)) * 64 + ((col >> 3) & 1) * 32 + (row & 31)) * 8;
.LBB0_245:
	v_ashrrev_i32_e32 v68, 5, v68
	v_ashrrev_i32_e32 v69, 31, v68
	s_andn2_b64 vcc, exec, s[54:55]
	v_lshlrev_b64 v[68:69], 5, v[68:69]
	s_cbranch_vccnz .LBB0_247
	s_lshr_b32 s25, s36, 4
	s_and_b32 s25, s25, 28
	v_or3_b32 v70, v169, s25, v68
	v_mov_b32_e32 v71, v69
	v_lshlrev_b64 v[70:71], 6, v[70:71]
	v_or_b32_e32 v70, v70, v170
	v_or_b32_e32 v70, v70, v140
	v_lshl_add_u64 v[70:71], v[70:71], 4, s[34:35]

; DI int pi32e(int r) { return (r & ~12) | ((r & 4) << 1) | ((r & 8) >> 1); }
;     DI void operator()(const f32x4 (&acc)[2][2][4][2], const Unit& u, int wr, int wc, int fr, int fq) const {
;     ...
;                     if (u.kind == 0) {
;                         const int isk = col >> 9, c = col & 511, rr = isk ? pi32e(row & 31) : (row & 31);
;                         dst = base + (size_t)isk * ((size_t)T * 512) + ((((size_t)(row >> 5) * 8 + (c >> 6)) * 4 + ((c & 63) >> 4)) * 64 + ((c >> 3) & 1) * 32 + rr) * 8;
;                     } else if (u.kind == 1) {
;                         dst = base + ((((size_t)(col >> 5) * 8 + (row >> 6)) * 4 + ((row & 63) >> 5) * 2 + ((col & 31) >> 4)) * 64 + ((col >> 3) & 1) * 32 + (row & 31)) * 8;
.LBB0_260:
	v_and_or_b32 v54, v48, 19, v145
	v_ashrrev_i32_e32 v48, 5, v48
	v_ashrrev_i32_e32 v49, 31, v48
	v_lshlrev_b64 v[48:49], 5, v[48:49]
	s_andn2_b64 vcc, exec, s[54:55]
	v_cndmask_b32_e64 v54, v54, v162, s[0:1]
	s_cbranch_vccnz .LBB0_262
	s_lshr_b32 s25, s36, 4
	s_and_b32 s25, s25, 28
	v_or3_b32 v52, v169, s25, v48
	v_mov_b32_e32 v53, v49
	v_lshlrev_b64 v[52:53], 6, v[52:53]
	v_or_b32_e32 v52, v52, v54
	v_or_b32_e32 v52, v52, v140
	v_lshl_add_u64 v[52:53], v[52:53], 4, s[34:35]

; DI int pi32e(int r) { return (r & ~12) | ((r & 4) << 1) | ((r & 8) >> 1); }
;     DI void operator()(const f32x4 (&acc)[2][2][4][2], const Unit& u, int wr, int wc, int fr, int fq) const {
;     ...
;                     if (u.kind == 0) {
;                         const int isk = col >> 9, c = col & 511, rr = isk ? pi32e(row & 31) : (row & 31);
;                         dst = base + (size_t)isk * ((size_t)T * 512) + ((((size_t)(row >> 5) * 8 + (c >> 6)) * 4 + ((c & 63) >> 4)) * 64 + ((c >> 3) & 1) * 32 + rr) * 8;
;                     } else if (u.kind == 1) {
;                         dst = base + ((((size_t)(col >> 5) * 8 + (row >> 6)) * 4 + ((row & 63) >> 5) * 2 + ((col & 31) >> 4)) * 64 + ((col >> 3) & 1) * 32 + (row & 31)) * 8;
.LBB0_275:
	v_ashrrev_i32_e32 v34, 5, v34
	v_ashrrev_i32_e32 v35, 31, v34
	s_andn2_b64 vcc, exec, s[54:55]
	v_lshlrev_b64 v[34:35], 5, v[34:35]
	s_cbranch_vccnz .LBB0_277
	s_lshr_b32 s25, s36, 4
	s_and_b32 s25, s25, 28
	v_or3_b32 v36, v169, s25, v34
	v_mov_b32_e32 v37, v35
	v_lshlrev_b64 v[36:37], 6, v[36:37]
	v_or_b32_e32 v36, v36, v170
	v_or_b32_e32 v36, v36, v140
	v_lshl_add_u64 v[36:37], v[36:37], 4, s[34:35]

; DI int pi32e(int r) { return (r & ~12) | ((r & 4) << 1) | ((r & 8) >> 1); }
;     DI void operator()(const f32x4 (&acc)[2][2][4][2], const Unit& u, int wr, int wc, int fr, int fq) const {
;     ...
;                     if (u.kind == 0) {
;                         const int isk = col >> 9, c = col & 511, rr = isk ? pi32e(row & 31) : (row & 31);
;                         dst = base + (size_t)isk * ((size_t)T * 512) + ((((size_t)(row >> 5) * 8 + (c >> 6)) * 4 + ((c & 63) >> 4)) * 64 + ((c >> 3) & 1) * 32 + rr) * 8;
;                     } else if (u.kind == 1) {
;                         dst = base + ((((size_t)(col >> 5) * 8 + (row >> 6)) * 4 + ((row & 63) >> 5) * 2 + ((col & 31) >> 4)) * 64 + ((col >> 3) & 1) * 32 + (row & 31)) * 8;
.LBB0_290:
	v_and_or_b32 v22, v16, 19, v145
	v_ashrrev_i32_e32 v16, 5, v16
	v_ashrrev_i32_e32 v17, 31, v16
	v_lshlrev_b64 v[16:17], 5, v[16:17]
	s_andn2_b64 vcc, exec, s[54:55]
	v_cndmask_b32_e64 v22, v22, v162, s[0:1]
	s_cbranch_vccnz .LBB0_292
	s_lshr_b32 s0, s36, 4
	s_and_b32 s0, s0, 28
	v_or3_b32 v20, v169, s0, v16
	v_mov_b32_e32 v21, v17
	v_lshlrev_b64 v[20:21], 6, v[20:21]
	v_or_b32_e32 v20, v20, v22
	v_or_b32_e32 v20, v20, v140
	v_lshl_add_u64 v[20:21], v[20:21], 4, s[34:35]
